# v36 + first four K-fragment LDS reads of the fused block issued at the loop header (speculative, when previous iteration was fused)
# baseline (speedup 1.0000x reference)
; #define LAS __attribute__((address_space(3)))
; #define MFMA32(a, b, c) __builtin_amdgcn_mfma_f32_32x32x16_bf16((a), (b), (c), 0, 0, 0)
; DI int perm32k(int i) { return (i & 0x13) | ((i & 8) >> 1) | ((i & 4) << 1); }
; DI void attn_unit(LAS unsigned char* lds, const bf16_t* __restrict__ Q, const bf16_t* __restrict__ Kg, const bf16_t* __restrict__ VT, bf16_t* __restrict__ MIX, int b, int h, int c0, int nq, int desc) {
;     ...
;   for (int t = 0; t < nt; ++t) {
;     const int buf = t & 1; const int tau = TAU(t), taun = TAU(t + 1);
;     ...
;       const LAS unsigned char* kb2 = lds + (buf ^ 1) * ATT_KB + perm32k(r31) * KROWB + 16 * hh;
;       __builtin_amdgcn_sched_barrier(0);
; #pragma unroll
;       for (int sx = 0; sx < 12; ++sx) { const bf16x8 a0 = *(const LAS bf16x8*)(kb2 + 32 * sx); const bf16x8 a1 = *(const LAS bf16x8*)(kb2 + 32 * KROWB + 32 * sx);
;         n0 = MFMA32(a0, qf[sx], n0); n1 = MFMA32(a1, qf[sx], n1);
.LBB0_539:
	s_add_i32 s98, s23, 131072
	s_cmp_eq_u32 s98, s99
	s_cbranch_scc0 .Lnoearly_LBB0_551
	s_add_i32 s98, s23, 0x101
	s_and_b32 s98, s98, 1
	s_xor_b32 s98, s98, 1
	s_mulk_i32 s98, 0x6400
	v_add_u32_e32 v242, s98, v208
	ds_read_b128 v[212:215], v242
	ds_read_b128 v[218:221], v242 offset:12800
	ds_read_b128 v[230:233], v242 offset:32
	ds_read_b128 v[234:237], v242 offset:12832

; #define LAS __attribute__((address_space(3)))
; #define MFMA32(a, b, c) __builtin_amdgcn_mfma_f32_32x32x16_bf16((a), (b), (c), 0, 0, 0)
; DI int perm32k(int i) { return (i & 0x13) | ((i & 8) >> 1) | ((i & 4) << 1); }
; DI void attn_unit(LAS unsigned char* lds, const bf16_t* __restrict__ Q, const bf16_t* __restrict__ Kg, const bf16_t* __restrict__ VT, bf16_t* __restrict__ MIX, int b, int h, int c0, int nq, int desc) {
;     ...
;       const LAS unsigned char* kb2 = lds + (buf ^ 1) * ATT_KB + perm32k(r31) * KROWB + 16 * hh;
;       __builtin_amdgcn_sched_barrier(0);
; #pragma unroll
;       for (int sx = 0; sx < 12; ++sx) { const bf16x8 a0 = *(const LAS bf16x8*)(kb2 + 32 * sx); const bf16x8 a1 = *(const LAS bf16x8*)(kb2 + 32 * KROWB + 32 * sx);
;         n0 = MFMA32(a0, qf[sx], n0); n1 = MFMA32(a1, qf[sx], n1);
; #pragma unroll
;         for (int j = 0; j < 3; ++j) { const int ei = 3 * sx + j; if (ei < 16) s0[ei] = __builtin_amdgcn_exp2f(s0[ei] - mrun); else if (ei < 32) s1[ei - 16] = __builtin_amdgcn_exp2f(s1[ei - 16] - mrun); }
;         __builtin_amdgcn_sched_barrier(0); }
.LBB0_551:
	s_xor_b32 s34, s12, 1
	s_mulk_i32 s34, 0x6400
	v_add_u32_e32 v223, s34, v208
	s_add_i32 s98, s23, 131072
	s_cmp_eq_u32 s98, s99
	s_cbranch_scc1 .Lskipr_LBB0_551
	ds_read_b128 v[212:215], v223
	ds_read_b128 v[218:221], v223 offset:12800
	ds_read_b128 v[230:233], v223 offset:32
	ds_read_b128 v[234:237], v223 offset:12832
.Lskipr_LBB0_551:
	v_sub_f32_e32 v82, v82, v211
	v_exp_f32_e32 v82, v82
	v_sub_f32_e32 v83, v83, v211
	v_exp_f32_e32 v83, v83
	v_sub_f32_e32 v84, v84, v211
	v_exp_f32_e32 v84, v84
	s_waitcnt lgkmcnt(3)
	v_mfma_f32_32x32x16_bf16 v[98:113], v[212:215], v[130:133], 0
	ds_read_b128 v[212:215], v223 offset:64
	v_sub_f32_e32 v85, v85, v211
	v_exp_f32_e32 v85, v85
	v_sub_f32_e32 v86, v86, v211
	v_exp_f32_e32 v86, v86
	s_waitcnt lgkmcnt(3)
	v_mfma_f32_32x32x16_bf16 v[114:129], v[218:221], v[130:133], 0
	ds_read_b128 v[218:221], v223 offset:12864
	v_sub_f32_e32 v87, v87, v211
	v_exp_f32_e32 v87, v87
	s_waitcnt lgkmcnt(3)
	v_mfma_f32_32x32x16_bf16 v[98:113], v[230:233], v[134:137], v[98:113]
	ds_read_b128 v[230:233], v223 offset:96
	v_sub_f32_e32 v88, v88, v211
	v_exp_f32_e32 v88, v88
	v_sub_f32_e32 v89, v89, v211
	v_exp_f32_e32 v89, v89
	s_waitcnt lgkmcnt(3)
	v_mfma_f32_32x32x16_bf16 v[114:129], v[234:237], v[134:137], v[114:129]
	ds_read_b128 v[234:237], v223 offset:12896
	v_sub_f32_e32 v90, v90, v211
	v_exp_f32_e32 v90, v90
	s_waitcnt lgkmcnt(3)
	v_mfma_f32_32x32x16_bf16 v[98:113], v[212:215], v[138:141], v[98:113]
	ds_read_b128 v[212:215], v223 offset:128
	v_sub_f32_e32 v91, v91, v211
	v_exp_f32_e32 v91, v91
	v_sub_f32_e32 v92, v92, v211
	v_exp_f32_e32 v92, v92
	s_waitcnt lgkmcnt(3)
	v_mfma_f32_32x32x16_bf16 v[114:129], v[218:221], v[138:141], v[114:129]
	ds_read_b128 v[218:221], v223 offset:12928
	v_sub_f32_e32 v93, v93, v211
	v_exp_f32_e32 v93, v93
	v_add_f32_e32 v238, v82, v86
	v_add_f32_e32 v239, v83, v87
	v_add_f32_e32 v240, v84, v88
	s_waitcnt lgkmcnt(3)
	v_mfma_f32_32x32x16_bf16 v[98:113], v[230:233], v[142:145], v[98:113]
	ds_read_b128 v[230:233], v223 offset:160
	v_sub_f32_e32 v94, v94, v211
	v_exp_f32_e32 v94, v94
	v_sub_f32_e32 v95, v95, v211
	v_exp_f32_e32 v95, v95
	s_waitcnt lgkmcnt(3)
	v_mfma_f32_32x32x16_bf16 v[114:129], v[234:237], v[142:145], v[114:129]
	ds_read_b128 v[234:237], v223 offset:12960
	v_sub_f32_e32 v96, v96, v211
	v_exp_f32_e32 v96, v96
	v_add_f32_e32 v241, v85, v89
	v_cvt_pk_bf16_f32 v82, v82, v83
	v_cvt_pk_bf16_f32 v83, v84, v85
	s_waitcnt lgkmcnt(3)
	v_mfma_f32_32x32x16_bf16 v[98:113], v[212:215], v[146:149], v[98:113]
	ds_read_b128 v[212:215], v223 offset:192
	v_sub_f32_e32 v97, v97, v211
	v_exp_f32_e32 v97, v97
	v_sub_f32_e32 v66, v66, v211
	v_exp_f32_e32 v66, v66
	s_waitcnt lgkmcnt(3)
	v_mfma_f32_32x32x16_bf16 v[114:129], v[218:221], v[146:149], v[114:129]
	ds_read_b128 v[218:221], v223 offset:12992
	v_sub_f32_e32 v67, v67, v211
	v_exp_f32_e32 v67, v67
	v_cvt_pk_bf16_f32 v84, v86, v87
	v_cvt_pk_bf16_f32 v85, v88, v89
	s_waitcnt lgkmcnt(3)
	v_mfma_f32_32x32x16_bf16 v[98:113], v[230:233], v[150:153], v[98:113]
	ds_read_b128 v[230:233], v223 offset:224
	v_sub_f32_e32 v68, v68, v211
	v_exp_f32_e32 v68, v68
	v_sub_f32_e32 v69, v69, v211
	v_exp_f32_e32 v69, v69
	s_waitcnt lgkmcnt(3)
	v_mfma_f32_32x32x16_bf16 v[114:129], v[234:237], v[150:153], v[114:129]
	ds_read_b128 v[234:237], v223 offset:13024
	v_sub_f32_e32 v70, v70, v211
	v_exp_f32_e32 v70, v70
	v_add_f32_e32 v238, v238, v90
	v_add_f32_e32 v239, v239, v91
	v_add_f32_e32 v240, v240, v92
	s_waitcnt lgkmcnt(3)
	v_mfma_f32_32x32x16_bf16 v[98:113], v[212:215], v[154:157], v[98:113]
	ds_read_b128 v[212:215], v223 offset:256
	v_sub_f32_e32 v71, v71, v211
	v_exp_f32_e32 v71, v71
	v_sub_f32_e32 v72, v72, v211
	v_exp_f32_e32 v72, v72
	s_waitcnt lgkmcnt(3)
; #define LAS __attribute__((address_space(3)))
; #define MFMA32(a, b, c) __builtin_amdgcn_mfma_f32_32x32x16_bf16((a), (b), (c), 0, 0, 0)
; DI bf16x8 pack8(const f32x16& x, int s) { u32x4 p; p.x = pk2(x[8 * s], x[8 * s + 1]); p.y = pk2(x[8 * s + 2], x[8 * s + 3]); p.z = pk2(x[8 * s + 4], x[8 * s + 5]); p.w = pk2(x[8 * s + 6], x[8 * s + 7]); return __builtin_bit_cast(bf16x8, p); }
; #define ATT_STOREK(buf) do { _Pragma("unroll") for (int i = 0; i < 3; ++i) *(LAS u32x4*)(lds + (buf) * ATT_KB + klo + 128 * i) = kreg[i]; } while (0)
; #define ATT_STOREV(buf) do { _Pragma("unroll") for (int i = 0; i < 2; ++i) *(LAS u32x4*)(lds + (buf) * ATT_VB + vlo + 64 * i) = vreg[i]; } while (0)
; DI void attn_unit(LAS unsigned char* lds, const bf16_t* __restrict__ Q, const bf16_t* __restrict__ Kg, const bf16_t* __restrict__ VT, bf16_t* __restrict__ MIX, int b, int h, int c0, int nq, int desc) {
;     ...
;       for (int sx = 0; sx < 12; ++sx) { const bf16x8 a0 = *(const LAS bf16x8*)(kb2 + 32 * sx); const bf16x8 a1 = *(const LAS bf16x8*)(kb2 + 32 * KROWB + 32 * sx);
;         n0 = MFMA32(a0, qf[sx], n0); n1 = MFMA32(a1, qf[sx], n1);
; #pragma unroll
;         for (int j = 0; j < 3; ++j) { const int ei = 3 * sx + j; if (ei < 16) s0[ei] = __builtin_amdgcn_exp2f(s0[ei] - mrun); else if (ei < 32) s1[ei - 16] = __builtin_amdgcn_exp2f(s1[ei - 16] - mrun); }
;         __builtin_amdgcn_sched_barrier(0); }
;       float ps = 0.f;
; #pragma unroll
;       for (int i = 0; i < 16; ++i) ps += s0[i] + s1[i];
;       lrun += ps;
;       bf16x8 pf[4]; pf[0] = pack8(s0, 0); pf[1] = pack8(s0, 1); pf[2] = pack8(s1, 0); pf[3] = pack8(s1, 1);
;       const LAS unsigned char* vb = lds + 2 * ATT_KB + buf * ATT_VB + r31 * HROW + 16 * hh;
; #pragma unroll
;       for (int kk = 0; kk < 4; ++kk)
; #pragma unroll
;         for (int d = 0; d < 4; ++d) { const bf16x8 a = *(const LAS bf16x8*)(vb + d * 32 * HROW + 32 * kk); O[d] = MFMA32(a, pf[kk], O[d]); }
;     ...
;     if (t + 2 < nt) ATT_STOREK(buf);
;     if (t + 1 < nt) ATT_STOREV(buf ^ 1);
	v_mfma_f32_32x32x16_bf16 v[114:129], v[218:221], v[154:157], v[114:129]
	ds_read_b128 v[218:221], v223 offset:13056
	v_sub_f32_e32 v73, v73, v211
	v_exp_f32_e32 v73, v73
	v_add_f32_e32 v241, v241, v93
	v_add_f32_e32 v238, v238, v94
	v_add_f32_e32 v239, v239, v95
	s_waitcnt lgkmcnt(3)
	v_mfma_f32_32x32x16_bf16 v[98:113], v[230:233], v[158:161], v[98:113]
	ds_read_b128 v[230:233], v223 offset:288
	v_sub_f32_e32 v74, v74, v211
	v_exp_f32_e32 v74, v74
	v_sub_f32_e32 v75, v75, v211
	v_exp_f32_e32 v75, v75
	s_waitcnt lgkmcnt(3)
	v_mfma_f32_32x32x16_bf16 v[114:129], v[234:237], v[158:161], v[114:129]
	ds_read_b128 v[234:237], v223 offset:13088
	v_sub_f32_e32 v76, v76, v211
	v_exp_f32_e32 v76, v76
	v_add_f32_e32 v240, v240, v96
	v_add_f32_e32 v241, v241, v97
	v_cvt_pk_bf16_f32 v90, v90, v91
	s_waitcnt lgkmcnt(3)
	v_mfma_f32_32x32x16_bf16 v[98:113], v[212:215], v[162:165], v[98:113]
	ds_read_b128 v[212:215], v223 offset:320
	v_sub_f32_e32 v77, v77, v211
	v_exp_f32_e32 v77, v77
	v_sub_f32_e32 v78, v78, v211
	v_exp_f32_e32 v78, v78
	s_waitcnt lgkmcnt(3)
	v_mfma_f32_32x32x16_bf16 v[114:129], v[218:221], v[162:165], v[114:129]
	ds_read_b128 v[218:221], v223 offset:13120
	v_sub_f32_e32 v79, v79, v211
	v_exp_f32_e32 v79, v79
	v_cvt_pk_bf16_f32 v91, v92, v93
	v_cvt_pk_bf16_f32 v92, v94, v95
	v_cvt_pk_bf16_f32 v93, v96, v97
	s_waitcnt lgkmcnt(3)
	v_mfma_f32_32x32x16_bf16 v[98:113], v[230:233], v[166:169], v[98:113]
	ds_read_b128 v[230:233], v223 offset:352
	v_sub_f32_e32 v80, v80, v211
	v_exp_f32_e32 v80, v80
	v_sub_f32_e32 v81, v81, v211
	v_exp_f32_e32 v81, v81
	s_waitcnt lgkmcnt(3)
	v_mfma_f32_32x32x16_bf16 v[114:129], v[234:237], v[166:169], v[114:129]
	ds_read_b128 v[234:237], v223 offset:13152
	v_add_f32_e32 v238, v238, v66
	v_add_f32_e32 v239, v239, v67
	v_add_f32_e32 v240, v240, v68
	s_waitcnt lgkmcnt(3)
	v_mfma_f32_32x32x16_bf16 v[98:113], v[212:215], v[170:173], v[98:113]
	s_mul_i32 s34, s12, 0x4800
	v_add_u32_e32 v223, s34, v209
	ds_read_b128 v[212:215], v223 offset:51200
	v_add_f32_e32 v241, v241, v69
	v_add_f32_e32 v238, v238, v70
	v_add_f32_e32 v239, v239, v71
	s_waitcnt lgkmcnt(3)
	v_mfma_f32_32x32x16_bf16 v[114:129], v[218:221], v[170:173], v[114:129]
	ds_read_b128 v[218:221], v223 offset:55808
	v_add_f32_e32 v240, v240, v72
	v_add_f32_e32 v241, v241, v73
	v_cvt_pk_bf16_f32 v66, v66, v67
	s_waitcnt lgkmcnt(3)
	v_mfma_f32_32x32x16_bf16 v[98:113], v[230:233], v[174:177], v[98:113]
	ds_read_b128 v[230:233], v223 offset:60416
	v_cvt_pk_bf16_f32 v67, v68, v69
	v_cvt_pk_bf16_f32 v68, v70, v71
	v_cvt_pk_bf16_f32 v69, v72, v73
	s_waitcnt lgkmcnt(3)
	v_mfma_f32_32x32x16_bf16 v[114:129], v[234:237], v[174:177], v[114:129]
	ds_read_b128 v[234:237], v223 offset:65024
	v_add_f32_e32 v238, v238, v74
	v_add_f32_e32 v239, v239, v75
	v_add_f32_e32 v240, v240, v76
	s_waitcnt lgkmcnt(3)
	v_mfma_f32_32x32x16_bf16 v[50:65], v[212:215], v[82:85], v[50:65]
	ds_read_b128 v[212:215], v223 offset:51232
	v_add_f32_e32 v241, v241, v77
	v_add_f32_e32 v238, v238, v78
	v_add_f32_e32 v239, v239, v79
	s_waitcnt lgkmcnt(3)
	v_mfma_f32_32x32x16_bf16 v[34:49], v[218:221], v[82:85], v[34:49]
	ds_read_b128 v[218:221], v223 offset:55840
	v_add_f32_e32 v240, v240, v80
	v_add_f32_e32 v241, v241, v81
	v_cvt_pk_bf16_f32 v74, v74, v75
	s_waitcnt lgkmcnt(3)
	v_mfma_f32_32x32x16_bf16 v[18:33], v[230:233], v[82:85], v[18:33]
	ds_read_b128 v[230:233], v223 offset:60448
	v_cvt_pk_bf16_f32 v75, v76, v77
	v_cvt_pk_bf16_f32 v76, v78, v79
	v_cvt_pk_bf16_f32 v77, v80, v81
	s_andn2_b64 vcc, exec, s[26:27]
	s_cbranch_vccnz .Lnok_LBB0_551
	s_mul_i32 s98, s12, 0x6400
	v_add_u32_e32 v229, s98, v205
	s_waitcnt vmcnt(2)
	ds_write_b128 v229, v[178:181]
	ds_write_b128 v229, v[182:185] offset:128
	ds_write_b128 v229, v[186:189] offset:256

; #define LAS __attribute__((address_space(3)))
; #define MFMA32(a, b, c) __builtin_amdgcn_mfma_f32_32x32x16_bf16((a), (b), (c), 0, 0, 0)
; DI int perm32k(int i) { return (i & 0x13) | ((i & 8) >> 1) | ((i & 4) << 1); }
; DI void attn_unit(LAS unsigned char* lds, const bf16_t* __restrict__ Q, const bf16_t* __restrict__ Kg, const bf16_t* __restrict__ VT, bf16_t* __restrict__ MIX, int b, int h, int c0, int nq, int desc) {
;     ...
;       const LAS unsigned char* kb2 = lds + (buf ^ 1) * ATT_KB + perm32k(r31) * KROWB + 16 * hh;
;       __builtin_amdgcn_sched_barrier(0);
; #pragma unroll
;       for (int sx = 0; sx < 12; ++sx) { const bf16x8 a0 = *(const LAS bf16x8*)(kb2 + 32 * sx); const bf16x8 a1 = *(const LAS bf16x8*)(kb2 + 32 * KROWB + 32 * sx);
;         n0 = MFMA32(a0, qf[sx], n0); n1 = MFMA32(a1, qf[sx], n1);
; #pragma unroll
;         for (int j = 0; j < 3; ++j) { const int ei = 3 * sx + j; if (ei < 16) s0[ei] = __builtin_amdgcn_exp2f(s0[ei] - mrun); else if (ei < 32) s1[ei - 16] = __builtin_amdgcn_exp2f(s1[ei - 16] - mrun); }
;         __builtin_amdgcn_sched_barrier(0); }
.LBB0_2562:
	s_xor_b32 s0, s12, 1
	s_mulk_i32 s0, 0x6400
	v_add_u32_e32 v223, s0, v208
	s_add_i32 s98, s23, 131072
	s_cmp_eq_u32 s98, s99
	s_cbranch_scc1 .Lskipr_LBB0_2562
	ds_read_b128 v[212:215], v223
	ds_read_b128 v[218:221], v223 offset:12800
	ds_read_b128 v[230:233], v223 offset:32
	ds_read_b128 v[234:237], v223 offset:12832
.Lskipr_LBB0_2562:
	v_sub_f32_e32 v82, v82, v211
	v_exp_f32_e32 v82, v82
	v_sub_f32_e32 v83, v83, v211
	v_exp_f32_e32 v83, v83
	v_sub_f32_e32 v84, v84, v211
	v_exp_f32_e32 v84, v84
	s_waitcnt lgkmcnt(3)
	v_mfma_f32_32x32x16_bf16 v[98:113], v[212:215], v[130:133], 0
	ds_read_b128 v[212:215], v223 offset:64
	v_sub_f32_e32 v85, v85, v211
	v_exp_f32_e32 v85, v85
	v_sub_f32_e32 v86, v86, v211
	v_exp_f32_e32 v86, v86
	s_waitcnt lgkmcnt(3)
	v_mfma_f32_32x32x16_bf16 v[114:129], v[218:221], v[130:133], 0
	ds_read_b128 v[218:221], v223 offset:12864
	v_sub_f32_e32 v87, v87, v211
	v_exp_f32_e32 v87, v87
	s_waitcnt lgkmcnt(3)
	v_mfma_f32_32x32x16_bf16 v[98:113], v[230:233], v[134:137], v[98:113]
	ds_read_b128 v[230:233], v223 offset:96
	v_sub_f32_e32 v88, v88, v211
	v_exp_f32_e32 v88, v88
	v_sub_f32_e32 v89, v89, v211
	v_exp_f32_e32 v89, v89
	s_waitcnt lgkmcnt(3)
	v_mfma_f32_32x32x16_bf16 v[114:129], v[234:237], v[134:137], v[114:129]
	ds_read_b128 v[234:237], v223 offset:12896
	v_sub_f32_e32 v90, v90, v211
	v_exp_f32_e32 v90, v90
	s_waitcnt lgkmcnt(3)
	v_mfma_f32_32x32x16_bf16 v[98:113], v[212:215], v[138:141], v[98:113]
	ds_read_b128 v[212:215], v223 offset:128
	v_sub_f32_e32 v91, v91, v211
	v_exp_f32_e32 v91, v91
	v_sub_f32_e32 v92, v92, v211
	v_exp_f32_e32 v92, v92
	s_waitcnt lgkmcnt(3)
	v_mfma_f32_32x32x16_bf16 v[114:129], v[218:221], v[138:141], v[114:129]
	ds_read_b128 v[218:221], v223 offset:12928
	v_sub_f32_e32 v93, v93, v211
	v_exp_f32_e32 v93, v93
	v_add_f32_e32 v238, v82, v86
	v_add_f32_e32 v239, v83, v87
	v_add_f32_e32 v240, v84, v88
	s_waitcnt lgkmcnt(3)
	v_mfma_f32_32x32x16_bf16 v[98:113], v[230:233], v[142:145], v[98:113]
	ds_read_b128 v[230:233], v223 offset:160
	v_sub_f32_e32 v94, v94, v211
	v_exp_f32_e32 v94, v94
	v_sub_f32_e32 v95, v95, v211
	v_exp_f32_e32 v95, v95
	s_waitcnt lgkmcnt(3)
	v_mfma_f32_32x32x16_bf16 v[114:129], v[234:237], v[142:145], v[114:129]
	ds_read_b128 v[234:237], v223 offset:12960
	v_sub_f32_e32 v96, v96, v211
	v_exp_f32_e32 v96, v96
	v_add_f32_e32 v241, v85, v89
	v_cvt_pk_bf16_f32 v82, v82, v83
	v_cvt_pk_bf16_f32 v83, v84, v85
	s_waitcnt lgkmcnt(3)
	v_mfma_f32_32x32x16_bf16 v[98:113], v[212:215], v[146:149], v[98:113]
	ds_read_b128 v[212:215], v223 offset:192
	v_sub_f32_e32 v97, v97, v211
	v_exp_f32_e32 v97, v97
	v_sub_f32_e32 v66, v66, v211
	v_exp_f32_e32 v66, v66
	s_waitcnt lgkmcnt(3)
	v_mfma_f32_32x32x16_bf16 v[114:129], v[218:221], v[146:149], v[114:129]
	ds_read_b128 v[218:221], v223 offset:12992
	v_sub_f32_e32 v67, v67, v211
	v_exp_f32_e32 v67, v67
	v_cvt_pk_bf16_f32 v84, v86, v87
	v_cvt_pk_bf16_f32 v85, v88, v89
	s_waitcnt lgkmcnt(3)
	v_mfma_f32_32x32x16_bf16 v[98:113], v[230:233], v[150:153], v[98:113]
	ds_read_b128 v[230:233], v223 offset:224
	v_sub_f32_e32 v68, v68, v211
	v_exp_f32_e32 v68, v68
	v_sub_f32_e32 v69, v69, v211
	v_exp_f32_e32 v69, v69
	s_waitcnt lgkmcnt(3)
	v_mfma_f32_32x32x16_bf16 v[114:129], v[234:237], v[150:153], v[114:129]
	ds_read_b128 v[234:237], v223 offset:13024
	v_sub_f32_e32 v70, v70, v211
	v_exp_f32_e32 v70, v70
	v_add_f32_e32 v238, v238, v90
	v_add_f32_e32 v239, v239, v91
	v_add_f32_e32 v240, v240, v92
	s_waitcnt lgkmcnt(3)
	v_mfma_f32_32x32x16_bf16 v[98:113], v[212:215], v[154:157], v[98:113]
	ds_read_b128 v[212:215], v223 offset:256
	v_sub_f32_e32 v71, v71, v211
	v_exp_f32_e32 v71, v71
	v_sub_f32_e32 v72, v72, v211
	v_exp_f32_e32 v72, v72
	s_waitcnt lgkmcnt(3)
; #define LAS __attribute__((address_space(3)))
; #define MFMA32(a, b, c) __builtin_amdgcn_mfma_f32_32x32x16_bf16((a), (b), (c), 0, 0, 0)
; DI bf16x8 pack8(const f32x16& x, int s) { u32x4 p; p.x = pk2(x[8 * s], x[8 * s + 1]); p.y = pk2(x[8 * s + 2], x[8 * s + 3]); p.z = pk2(x[8 * s + 4], x[8 * s + 5]); p.w = pk2(x[8 * s + 6], x[8 * s + 7]); return __builtin_bit_cast(bf16x8, p); }
; #define ATT_STOREK(buf) do { _Pragma("unroll") for (int i = 0; i < 3; ++i) *(LAS u32x4*)(lds + (buf) * ATT_KB + klo + 128 * i) = kreg[i]; } while (0)
; #define ATT_STOREV(buf) do { _Pragma("unroll") for (int i = 0; i < 2; ++i) *(LAS u32x4*)(lds + (buf) * ATT_VB + vlo + 64 * i) = vreg[i]; } while (0)
; DI void attn_unit(LAS unsigned char* lds, const bf16_t* __restrict__ Q, const bf16_t* __restrict__ Kg, const bf16_t* __restrict__ VT, bf16_t* __restrict__ MIX, int b, int h, int c0, int nq, int desc) {
;     ...
;       for (int sx = 0; sx < 12; ++sx) { const bf16x8 a0 = *(const LAS bf16x8*)(kb2 + 32 * sx); const bf16x8 a1 = *(const LAS bf16x8*)(kb2 + 32 * KROWB + 32 * sx);
;         n0 = MFMA32(a0, qf[sx], n0); n1 = MFMA32(a1, qf[sx], n1);
; #pragma unroll
;         for (int j = 0; j < 3; ++j) { const int ei = 3 * sx + j; if (ei < 16) s0[ei] = __builtin_amdgcn_exp2f(s0[ei] - mrun); else if (ei < 32) s1[ei - 16] = __builtin_amdgcn_exp2f(s1[ei - 16] - mrun); }
;         __builtin_amdgcn_sched_barrier(0); }
;       float ps = 0.f;
; #pragma unroll
;       for (int i = 0; i < 16; ++i) ps += s0[i] + s1[i];
;       lrun += ps;
;       bf16x8 pf[4]; pf[0] = pack8(s0, 0); pf[1] = pack8(s0, 1); pf[2] = pack8(s1, 0); pf[3] = pack8(s1, 1);
;       const LAS unsigned char* vb = lds + 2 * ATT_KB + buf * ATT_VB + r31 * HROW + 16 * hh;
; #pragma unroll
;       for (int kk = 0; kk < 4; ++kk)
; #pragma unroll
;         for (int d = 0; d < 4; ++d) { const bf16x8 a = *(const LAS bf16x8*)(vb + d * 32 * HROW + 32 * kk); O[d] = MFMA32(a, pf[kk], O[d]); }
;     ...
;     if (t + 2 < nt) ATT_STOREK(buf);
;     if (t + 1 < nt) ATT_STOREV(buf ^ 1);
	v_mfma_f32_32x32x16_bf16 v[114:129], v[218:221], v[154:157], v[114:129]
	ds_read_b128 v[218:221], v223 offset:13056
	v_sub_f32_e32 v73, v73, v211
	v_exp_f32_e32 v73, v73
	v_add_f32_e32 v241, v241, v93
	v_add_f32_e32 v238, v238, v94
	v_add_f32_e32 v239, v239, v95
	s_waitcnt lgkmcnt(3)
	v_mfma_f32_32x32x16_bf16 v[98:113], v[230:233], v[158:161], v[98:113]
	ds_read_b128 v[230:233], v223 offset:288
	v_sub_f32_e32 v74, v74, v211
	v_exp_f32_e32 v74, v74
	v_sub_f32_e32 v75, v75, v211
	v_exp_f32_e32 v75, v75
	s_waitcnt lgkmcnt(3)
	v_mfma_f32_32x32x16_bf16 v[114:129], v[234:237], v[158:161], v[114:129]
	ds_read_b128 v[234:237], v223 offset:13088
	v_sub_f32_e32 v76, v76, v211
	v_exp_f32_e32 v76, v76
	v_add_f32_e32 v240, v240, v96
	v_add_f32_e32 v241, v241, v97
	v_cvt_pk_bf16_f32 v90, v90, v91
	s_waitcnt lgkmcnt(3)
	v_mfma_f32_32x32x16_bf16 v[98:113], v[212:215], v[162:165], v[98:113]
	ds_read_b128 v[212:215], v223 offset:320
	v_sub_f32_e32 v77, v77, v211
	v_exp_f32_e32 v77, v77
	v_sub_f32_e32 v78, v78, v211
	v_exp_f32_e32 v78, v78
	s_waitcnt lgkmcnt(3)
	v_mfma_f32_32x32x16_bf16 v[114:129], v[218:221], v[162:165], v[114:129]
	ds_read_b128 v[218:221], v223 offset:13120
	v_sub_f32_e32 v79, v79, v211
	v_exp_f32_e32 v79, v79
	v_cvt_pk_bf16_f32 v91, v92, v93
	v_cvt_pk_bf16_f32 v92, v94, v95
	v_cvt_pk_bf16_f32 v93, v96, v97
	s_waitcnt lgkmcnt(3)
	v_mfma_f32_32x32x16_bf16 v[98:113], v[230:233], v[166:169], v[98:113]
	ds_read_b128 v[230:233], v223 offset:352
	v_sub_f32_e32 v80, v80, v211
	v_exp_f32_e32 v80, v80
	v_sub_f32_e32 v81, v81, v211
	v_exp_f32_e32 v81, v81
	s_waitcnt lgkmcnt(3)
	v_mfma_f32_32x32x16_bf16 v[114:129], v[234:237], v[166:169], v[114:129]
	ds_read_b128 v[234:237], v223 offset:13152
	v_add_f32_e32 v238, v238, v66
	v_add_f32_e32 v239, v239, v67
	v_add_f32_e32 v240, v240, v68
	s_waitcnt lgkmcnt(3)
	v_mfma_f32_32x32x16_bf16 v[98:113], v[212:215], v[170:173], v[98:113]
	s_mul_i32 s0, s12, 0x4800
	v_add_u32_e32 v223, s0, v209
	ds_read_b128 v[212:215], v223 offset:51200
	v_add_f32_e32 v241, v241, v69
	v_add_f32_e32 v238, v238, v70
	v_add_f32_e32 v239, v239, v71
	s_waitcnt lgkmcnt(3)
	v_mfma_f32_32x32x16_bf16 v[114:129], v[218:221], v[170:173], v[114:129]
	ds_read_b128 v[218:221], v223 offset:55808
	v_add_f32_e32 v240, v240, v72
	v_add_f32_e32 v241, v241, v73
	v_cvt_pk_bf16_f32 v66, v66, v67
	s_waitcnt lgkmcnt(3)
	v_mfma_f32_32x32x16_bf16 v[98:113], v[230:233], v[174:177], v[98:113]
	ds_read_b128 v[230:233], v223 offset:60416
	v_cvt_pk_bf16_f32 v67, v68, v69
	v_cvt_pk_bf16_f32 v68, v70, v71
	v_cvt_pk_bf16_f32 v69, v72, v73
	s_waitcnt lgkmcnt(3)
	v_mfma_f32_32x32x16_bf16 v[114:129], v[234:237], v[174:177], v[114:129]
	ds_read_b128 v[234:237], v223 offset:65024
	v_add_f32_e32 v238, v238, v74
	v_add_f32_e32 v239, v239, v75
	v_add_f32_e32 v240, v240, v76
	s_waitcnt lgkmcnt(3)
	v_mfma_f32_32x32x16_bf16 v[50:65], v[212:215], v[82:85], v[50:65]
	ds_read_b128 v[212:215], v223 offset:51232
	v_add_f32_e32 v241, v241, v77
	v_add_f32_e32 v238, v238, v78
	v_add_f32_e32 v239, v239, v79
	s_waitcnt lgkmcnt(3)
	v_mfma_f32_32x32x16_bf16 v[34:49], v[218:221], v[82:85], v[34:49]
	ds_read_b128 v[218:221], v223 offset:55840
	v_add_f32_e32 v240, v240, v80
	v_add_f32_e32 v241, v241, v81
	v_cvt_pk_bf16_f32 v74, v74, v75
	s_waitcnt lgkmcnt(3)
	v_mfma_f32_32x32x16_bf16 v[18:33], v[230:233], v[82:85], v[18:33]
	ds_read_b128 v[230:233], v223 offset:60448
	v_cvt_pk_bf16_f32 v75, v76, v77
	v_cvt_pk_bf16_f32 v76, v78, v79
	v_cvt_pk_bf16_f32 v77, v80, v81
	s_andn2_b64 vcc, exec, s[26:27]
	s_cbranch_vccnz .Lnok_LBB0_2562
	s_mul_i32 s98, s12, 0x6400
	v_add_u32_e32 v229, s98, v205
	s_waitcnt vmcnt(2)
	ds_write_b128 v229, v[178:181]
	ds_write_b128 v229, v[182:185] offset:128
	ds_write_b128 v229, v[186:189] offset:256
